# MLA fast path: H1 half takes its per-step barrier after the MFMA-free top of the block (address calc, init broadcast, first exps), H1 boost kept
# speedup vs baseline: 1.0018x; 1.0018x over previous
; #define LAS __attribute__((address_space(3)))
; DI unsigned cvt_pk(float lo, float hi) { unsigned r; asm volatile("v_cvt_pk_bf16_f32 %0, %1, %2" : "=v"(r) : "v"(lo), "v"(hi)); return r; }
; DI float fexp2(float x) { return __builtin_amdgcn_exp2f(x); }
; template <int DK, int DV, int MODE> ...
;     ...
;   auto part2 = [&](f32x16 (&st)[2], int t) __attribute__((always_inline)) {
;     float ps0 = 0.f, ps1 = 0.f, ps2 = 0.f, ps3 = 0.f;
; #pragma unroll
;     for (int kb = 0; kb < 2; ++kb)
; #pragma unroll
;       for (int i = 0; i < 16; i += 4) {
;         const float p0 = fexp2(st[kb][i]), p1 = fexp2(st[kb][i + 1]), p2 = fexp2(st[kb][i + 2]), p3 = fexp2(st[kb][i + 3]);
;         st[kb][i] = p0; st[kb][i + 1] = p1; st[kb][i + 2] = p2; st[kb][i + 3] = p3; ps0 += p0; ps1 += p1; ps2 += p2; ps3 += p3;
;       }
;     lsum += (ps0 + ps1) + (ps2 + ps3);
;     bf16x8 pf[2][2];
; #pragma unroll
;     for (int kb = 0; kb < 2; ++kb)
; #pragma unroll
;       for (int s = 0; s < 2; ++s) { u32x4 pp; pp.x = cvt_pk(st[kb][8 * s], st[kb][8 * s + 1]); pp.y = cvt_pk(st[kb][8 * s + 2], st[kb][8 * s + 3]); pp.z = cvt_pk(st[kb][8 * s + 4], st[kb][8 * s + 5]); pp.w = cvt_pk(st[kb][8 * s + 6], st[kb][8 * s + 7]); pf[kb][s] = __builtin_bit_cast(bf16x8, pp); }
; #pragma unroll
;     for (int db = 0; db < DV / 32; ++db)
; #pragma unroll
;       for (int kb = 0; kb < 2; ++kb)
; #pragma unroll
;         for (int s = 0; s < 2; ++s) {
;           if (MODE == 1 && ((kb == 1 && s == 1 && cwu == 0) || (kb == 0 && s == 0 && cwu != 0))) continue;
;           const bf16x8 vf = *(const LAS bf16x8*)(lds + ATT_VB + (t & 3) * VBUF + (32 * db + r) * VSTR + (2 * kb + s) * 32 + hh * 16);
;           O[db] = __builtin_amdgcn_mfma_f32_32x32x16_bf16(vf, pf[kb][s], O[db], 0, 0, 0);
;         }
.Lf_da:
	s_setprio 1
	s_add_i32 s25, s19, -4
	s_and_b32 s21, s25, 3
	s_mul_i32 s26, s21, 0x3400
	s_and_b32 s23, s23, 2
	v_add_u32_e32 v252, s26, v160
	s_mul_i32 s26, s23, 0x2400
	ds_read_b128 v[196:199], v252
	ds_read_b128 v[200:203], v252 offset:32
	ds_read_b128 v[216:219], v252 offset:64
	ds_read_b128 v[230:233], v252 offset:96
	ds_read_b128 v[234:237], v252 offset:128
	ds_read_b128 v[244:247], v252 offset:160
	v_add_u32_e32 v243, s26, v163
	v_add_u32_e32 v0, 64, v167
	v_cmp_gt_i32_e32 vcc, s78, v0
	v_exp_f32_e32 v50, v50
	v_exp_f32_e32 v51, v51
	v_cndmask_b32_e32 v66, 0, v158, vcc
	v_cmp_lt_i32_e32 vcc, s77, v0
	v_exp_f32_e32 v52, v52
	v_exp_f32_e32 v53, v53
	v_cndmask_b32_e32 v0, v66, v159, vcc
	v_cmp_neq_f32_e32 vcc, s53, v143
	v_exp_f32_e32 v54, v54
	v_exp_f32_e32 v55, v55
	v_cndmask_b32_e32 v144, 0, v143, vcc
	v_sub_f32_e32 v66, v0, v144
	v_mov_b32_e32 v67, v66
	v_mov_b32_e32 v68, v66
	v_mov_b32_e32 v69, v66
	v_mov_b32_e32 v70, v66
	v_mov_b32_e32 v71, v66
	v_mov_b32_e32 v72, v66
	v_mov_b32_e32 v73, v66
	v_mov_b32_e32 v74, v66
	v_mov_b32_e32 v75, v66
	v_mov_b32_e32 v76, v66
	v_mov_b32_e32 v77, v66
	v_mov_b32_e32 v78, v66
	v_mov_b32_e32 v79, v66
	v_mov_b32_e32 v80, v66
	v_mov_b32_e32 v81, v66
	v_exp_f32_e32 v56, v56
	v_exp_f32_e32 v57, v57
	s_cmp_eq_u32 s32, 0
	s_cbranch_scc1 .Lfb_a0
	s_waitcnt lgkmcnt(6)
	s_barrier
	s_setprio 2
.Lfb_a0:
	s_waitcnt lgkmcnt(5)
	v_mfma_f32_32x32x16_bf16 v[82:97], v[196:199], v[98:101], v[66:81]
	ds_read_b128 v[196:199], v252 offset:6656
	v_exp_f32_e32 v58, v58
	v_exp_f32_e32 v59, v59
	v_exp_f32_e32 v60, v60
	v_exp_f32_e32 v61, v61
	s_waitcnt lgkmcnt(5)
	v_mfma_f32_32x32x16_bf16 v[82:97], v[200:203], v[102:105], v[82:97]
	ds_read_b128 v[200:203], v252 offset:6688
	v_exp_f32_e32 v62, v62
	v_exp_f32_e32 v63, v63
	v_exp_f32_e32 v64, v64
	v_exp_f32_e32 v65, v65
	s_waitcnt lgkmcnt(5)
	v_mfma_f32_32x32x16_bf16 v[82:97], v[216:219], v[106:109], v[82:97]
	ds_read_b128 v[216:219], v252 offset:6720
	v_exp_f32_e32 v34, v34
	v_exp_f32_e32 v35, v35
	v_cvt_pk_bf16_f32 v168, v50, v51
	v_exp_f32_e32 v36, v36
	s_waitcnt lgkmcnt(5)
	v_mfma_f32_32x32x16_bf16 v[82:97], v[230:233], v[110:113], v[82:97]
	ds_read_b128 v[230:233], v252 offset:6752
	v_exp_f32_e32 v37, v37
	v_cvt_pk_bf16_f32 v169, v52, v53
	v_exp_f32_e32 v38, v38
	v_exp_f32_e32 v39, v39
	s_waitcnt lgkmcnt(5)
	v_mfma_f32_32x32x16_bf16 v[82:97], v[234:237], v[114:117], v[82:97]
	ds_read_b128 v[234:237], v252 offset:6784
	v_cvt_pk_bf16_f32 v170, v54, v55
	v_exp_f32_e32 v40, v40
	v_exp_f32_e32 v41, v41
	v_cvt_pk_bf16_f32 v171, v56, v57
	v_exp_f32_e32 v42, v42
	s_waitcnt lgkmcnt(5)
	v_mfma_f32_32x32x16_bf16 v[82:97], v[244:247], v[118:121], v[82:97]
	ds_read_b128 v[244:247], v252 offset:6816
	v_exp_f32_e32 v43, v43
	v_cvt_pk_bf16_f32 v180, v58, v59
	v_exp_f32_e32 v44, v44
	v_exp_f32_e32 v45, v45
	s_waitcnt lgkmcnt(5)
	v_mfma_f32_32x32x16_bf16 v[66:81], v[196:199], v[98:101], v[66:81]
	ds_read_b128 v[196:199], v243 offset:53248
	v_cvt_pk_bf16_f32 v181, v60, v61
	v_exp_f32_e32 v46, v46
	v_exp_f32_e32 v47, v47
	v_cvt_pk_bf16_f32 v182, v62, v63
	v_exp_f32_e32 v48, v48
	s_waitcnt lgkmcnt(5)
	v_mfma_f32_32x32x16_bf16 v[66:81], v[200:203], v[102:105], v[66:81]
	ds_read_b128 v[200:203], v243 offset:57856
	v_exp_f32_e32 v49, v49
	v_cvt_pk_bf16_f32 v183, v64, v65
	v_add_f32_e32 v172, v50, v54
	v_add_f32_e32 v173, v51, v55
	v_add_f32_e32 v176, v52, v56
	v_add_f32_e32 v179, v53, v57
	s_waitcnt lgkmcnt(5)
	v_mfma_f32_32x32x16_bf16 v[66:81], v[216:219], v[106:109], v[66:81]
	ds_read_b128 v[216:219], v243 offset:53280
	v_add_f32_e32 v172, v58, v172
	v_add_f32_e32 v173, v59, v173
	v_add_f32_e32 v176, v60, v176
	v_add_f32_e32 v179, v61, v179
	v_add_f32_e32 v172, v62, v172
	v_add_f32_e32 v173, v63, v173
	v_add_f32_e32 v176, v64, v176
	s_waitcnt lgkmcnt(5)
	v_mfma_f32_32x32x16_bf16 v[66:81], v[230:233], v[110:113], v[66:81]
	ds_read_b128 v[230:233], v243 offset:57888
	v_add_f32_e32 v179, v65, v179
	v_cvt_pk_bf16_f32 v184, v34, v35
	v_cvt_pk_bf16_f32 v185, v36, v37
	v_cvt_pk_bf16_f32 v186, v38, v39
	v_cvt_pk_bf16_f32 v187, v40, v41
	v_cvt_pk_bf16_f32 v188, v42, v43
	v_cvt_pk_bf16_f32 v189, v44, v45
	s_waitcnt lgkmcnt(5)
	v_mfma_f32_32x32x16_bf16 v[66:81], v[234:237], v[114:117], v[66:81]
	ds_read_b128 v[234:237], v243 offset:53312
	v_cvt_pk_bf16_f32 v190, v46, v47
	v_cvt_pk_bf16_f32 v191, v48, v49
	v_add_f32_e32 v172, v34, v172
	v_add_f32_e32 v173, v35, v173
	v_add_f32_e32 v176, v36, v176
	v_add_f32_e32 v179, v37, v179
	v_add_f32_e32 v172, v38, v172
	s_waitcnt lgkmcnt(5)
	v_mfma_f32_32x32x16_bf16 v[66:81], v[244:247], v[118:121], v[66:81]
	ds_read_b128 v[244:247], v243 offset:57920
	v_add_f32_e32 v173, v39, v173
	v_add_f32_e32 v176, v40, v176
	v_add_f32_e32 v179, v41, v179
	v_add_f32_e32 v172, v42, v172
	v_add_f32_e32 v173, v43, v173
	v_add_f32_e32 v176, v44, v176
	v_add_f32_e32 v179, v45, v179
	s_waitcnt lgkmcnt(5)
	v_mfma_f32_32x32x16_bf16 v[18:33], v[196:199], v[168:171], v[18:33]
	ds_read_b128 v[196:199], v243 offset:53344
	v_add_f32_e32 v172, v46, v172
	v_add_f32_e32 v173, v47, v173
	v_add_f32_e32 v176, v48, v176
	v_add_f32_e32 v179, v49, v179
	v_add_f32_e32 v172, v172, v173
	v_add_f32_e32 v176, v176, v179
	v_max3_f32 v248, v82, v83, v84
	s_waitcnt lgkmcnt(5)
	v_mfma_f32_32x32x16_bf16 v[2:17], v[200:203], v[168:171], v[2:17]
	ds_read_b128 v[200:203], v243 offset:57952
	v_max3_f32 v249, v89, v90, v91
	v_max3_f32 v248, v248, v85, v86
	v_max3_f32 v249, v249, v92, v93
	v_max3_f32 v248, v248, v87, v88
	v_max3_f32 v249, v249, v94, v95
	s_waitcnt lgkmcnt(5)
	v_mfma_f32_32x32x16_bf16 v[18:33], v[216:219], v[180:183], v[18:33]
	v_max3_f32 v250, v66, v67, v68
	v_max3_f32 v251, v73, v74, v75
	v_max3_f32 v250, v250, v69, v70
	v_max3_f32 v251, v251, v76, v77
	v_max3_f32 v250, v250, v71, v72
	v_max3_f32 v251, v251, v78, v79
	v_max3_f32 v248, v248, v249, v96
	s_waitcnt lgkmcnt(4)
	v_mfma_f32_32x32x16_bf16 v[2:17], v[230:233], v[180:183], v[2:17]
	v_max3_f32 v250, v250, v251, v80
	v_max3_f32 v248, v248, v97, v81
	v_max_f32_e32 v248, v248, v250
	v_mov_b32_e32 v249, v248
	s_waitcnt lgkmcnt(3)
	v_mfma_f32_32x32x16_bf16 v[18:33], v[234:237], v[184:187], v[18:33]
	s_waitcnt lgkmcnt(2)
	v_mfma_f32_32x32x16_bf16 v[2:17], v[244:247], v[184:187], v[2:17]
	s_waitcnt lgkmcnt(1)
	v_mfma_f32_32x32x16_bf16 v[18:33], v[196:199], v[188:191], v[18:33]
	s_waitcnt lgkmcnt(0)
	v_mfma_f32_32x32x16_bf16 v[2:17], v[200:203], v[188:191], v[2:17]
	v_add_f32_e32 v0, v172, v176
	v_add_f32_e32 v161, v161, v0
	v_permlane32_swap_b32 v248, v249
	v_max_f32_e32 v174, v248, v249
	s_setprio 0
	s_cmp_lg_u32 s32, 0
	s_cbranch_scc1 .Lfb_a1
	s_waitcnt lgkmcnt(0)
	s_barrier

; #define LAS __attribute__((address_space(3)))
; DI unsigned cvt_pk(float lo, float hi) { unsigned r; asm volatile("v_cvt_pk_bf16_f32 %0, %1, %2" : "=v"(r) : "v"(lo), "v"(hi)); return r; }
; DI float fexp2(float x) { return __builtin_amdgcn_exp2f(x); }
; template <int DK, int DV, int MODE> ...
;     ...
;   auto part2 = [&](f32x16 (&st)[2], int t) __attribute__((always_inline)) {
;     float ps0 = 0.f, ps1 = 0.f, ps2 = 0.f, ps3 = 0.f;
; #pragma unroll
;     for (int kb = 0; kb < 2; ++kb)
; #pragma unroll
;       for (int i = 0; i < 16; i += 4) {
;         const float p0 = fexp2(st[kb][i]), p1 = fexp2(st[kb][i + 1]), p2 = fexp2(st[kb][i + 2]), p3 = fexp2(st[kb][i + 3]);
;         st[kb][i] = p0; st[kb][i + 1] = p1; st[kb][i + 2] = p2; st[kb][i + 3] = p3; ps0 += p0; ps1 += p1; ps2 += p2; ps3 += p3;
;       }
;     lsum += (ps0 + ps1) + (ps2 + ps3);
;     bf16x8 pf[2][2];
; #pragma unroll
;     for (int kb = 0; kb < 2; ++kb)
; #pragma unroll
;       for (int s = 0; s < 2; ++s) { u32x4 pp; pp.x = cvt_pk(st[kb][8 * s], st[kb][8 * s + 1]); pp.y = cvt_pk(st[kb][8 * s + 2], st[kb][8 * s + 3]); pp.z = cvt_pk(st[kb][8 * s + 4], st[kb][8 * s + 5]); pp.w = cvt_pk(st[kb][8 * s + 6], st[kb][8 * s + 7]); pf[kb][s] = __builtin_bit_cast(bf16x8, pp); }
; #pragma unroll
;     for (int db = 0; db < DV / 32; ++db)
; #pragma unroll
;       for (int kb = 0; kb < 2; ++kb)
; #pragma unroll
;         for (int s = 0; s < 2; ++s) {
;           if (MODE == 1 && ((kb == 1 && s == 1 && cwu == 0) || (kb == 0 && s == 0 && cwu != 0))) continue;
;           const bf16x8 vf = *(const LAS bf16x8*)(lds + ATT_VB + (t & 3) * VBUF + (32 * db + r) * VSTR + (2 * kb + s) * 32 + hh * 16);
;           O[db] = __builtin_amdgcn_mfma_f32_32x32x16_bf16(vf, pf[kb][s], O[db], 0, 0, 0);
;         }
.Lf_db:
	s_setprio 1
	s_and_b32 s22, s20, 2
	s_mulk_i32 s22, 0x3400
	s_mulk_i32 s21, 0x2400
	v_add_u32_e32 v252, s22, v160
	ds_read_b128 v[196:199], v252
	ds_read_b128 v[200:203], v252 offset:32
	ds_read_b128 v[216:219], v252 offset:64
	ds_read_b128 v[230:233], v252 offset:96
	ds_read_b128 v[234:237], v252 offset:128
	ds_read_b128 v[244:247], v252 offset:160
	v_add_u32_e32 v243, s21, v163
	v_add_u32_e32 v0, 0x80, v167
	v_cmp_gt_i32_e32 vcc, s78, v0
	v_exp_f32_e32 v82, v82
	v_exp_f32_e32 v83, v83
	v_cndmask_b32_e32 v34, 0, v158, vcc
	v_cmp_lt_i32_e32 vcc, s77, v0
	v_exp_f32_e32 v84, v84
	v_exp_f32_e32 v85, v85
	v_cndmask_b32_e32 v0, v34, v159, vcc
	v_cmp_neq_f32_e32 vcc, s53, v143
	v_exp_f32_e32 v86, v86
	v_exp_f32_e32 v87, v87
	v_cndmask_b32_e32 v142, 0, v143, vcc
	v_sub_f32_e32 v34, v0, v142
	v_mov_b32_e32 v35, v34
	v_mov_b32_e32 v36, v34
	v_mov_b32_e32 v37, v34
	v_mov_b32_e32 v38, v34
	v_mov_b32_e32 v39, v34
	v_mov_b32_e32 v40, v34
	v_mov_b32_e32 v41, v34
	v_mov_b32_e32 v42, v34
	v_mov_b32_e32 v43, v34
	v_mov_b32_e32 v44, v34
	v_mov_b32_e32 v45, v34
	v_mov_b32_e32 v46, v34
	v_mov_b32_e32 v47, v34
	v_mov_b32_e32 v48, v34
	v_mov_b32_e32 v49, v34
	v_exp_f32_e32 v88, v88
	v_exp_f32_e32 v89, v89
	s_cmp_eq_u32 s32, 0
	s_cbranch_scc1 .Lfb_b0
	s_waitcnt lgkmcnt(6)
	s_barrier
	s_setprio 2
.Lfb_b0:
	s_waitcnt lgkmcnt(5)
	v_mfma_f32_32x32x16_bf16 v[50:65], v[196:199], v[98:101], v[34:49]
	ds_read_b128 v[196:199], v252 offset:6656
	v_exp_f32_e32 v90, v90
	v_exp_f32_e32 v91, v91
	v_exp_f32_e32 v92, v92
	v_exp_f32_e32 v93, v93
	s_waitcnt lgkmcnt(5)
	v_mfma_f32_32x32x16_bf16 v[50:65], v[200:203], v[102:105], v[50:65]
	ds_read_b128 v[200:203], v252 offset:6688
	v_exp_f32_e32 v94, v94
	v_exp_f32_e32 v95, v95
	v_exp_f32_e32 v96, v96
	v_exp_f32_e32 v97, v97
	s_waitcnt lgkmcnt(5)
	v_mfma_f32_32x32x16_bf16 v[50:65], v[216:219], v[106:109], v[50:65]
	ds_read_b128 v[216:219], v252 offset:6720
	v_exp_f32_e32 v66, v66
	v_exp_f32_e32 v67, v67
	v_cvt_pk_bf16_f32 v168, v82, v83
	v_exp_f32_e32 v68, v68
	s_waitcnt lgkmcnt(5)
	v_mfma_f32_32x32x16_bf16 v[50:65], v[230:233], v[110:113], v[50:65]
	ds_read_b128 v[230:233], v252 offset:6752
	v_exp_f32_e32 v69, v69
	v_cvt_pk_bf16_f32 v169, v84, v85
	v_exp_f32_e32 v70, v70
	v_exp_f32_e32 v71, v71
	s_waitcnt lgkmcnt(5)
	v_mfma_f32_32x32x16_bf16 v[50:65], v[234:237], v[114:117], v[50:65]
	ds_read_b128 v[234:237], v252 offset:6784
	v_cvt_pk_bf16_f32 v170, v86, v87
	v_exp_f32_e32 v72, v72
	v_exp_f32_e32 v73, v73
	v_cvt_pk_bf16_f32 v171, v88, v89
	v_exp_f32_e32 v74, v74
	s_waitcnt lgkmcnt(5)
	v_mfma_f32_32x32x16_bf16 v[50:65], v[244:247], v[118:121], v[50:65]
	ds_read_b128 v[244:247], v252 offset:6816
	v_exp_f32_e32 v75, v75
	v_cvt_pk_bf16_f32 v180, v90, v91
	v_exp_f32_e32 v76, v76
	v_exp_f32_e32 v77, v77
	s_waitcnt lgkmcnt(5)
	v_mfma_f32_32x32x16_bf16 v[34:49], v[196:199], v[98:101], v[34:49]
	ds_read_b128 v[196:199], v243 offset:53248
	v_cvt_pk_bf16_f32 v181, v92, v93
	v_exp_f32_e32 v78, v78
	v_exp_f32_e32 v79, v79
	v_cvt_pk_bf16_f32 v182, v94, v95
	v_exp_f32_e32 v80, v80
	s_waitcnt lgkmcnt(5)
	v_mfma_f32_32x32x16_bf16 v[34:49], v[200:203], v[102:105], v[34:49]
	ds_read_b128 v[200:203], v243 offset:57856
	v_exp_f32_e32 v81, v81
	v_cvt_pk_bf16_f32 v183, v96, v97
	v_add_f32_e32 v172, v82, v86
	v_add_f32_e32 v173, v83, v87
	v_add_f32_e32 v176, v84, v88
	v_add_f32_e32 v179, v85, v89
	s_waitcnt lgkmcnt(5)
	v_mfma_f32_32x32x16_bf16 v[34:49], v[216:219], v[106:109], v[34:49]
	ds_read_b128 v[216:219], v243 offset:53280
	v_add_f32_e32 v172, v90, v172
	v_add_f32_e32 v173, v91, v173
	v_add_f32_e32 v176, v92, v176
	v_add_f32_e32 v179, v93, v179
	v_add_f32_e32 v172, v94, v172
	v_add_f32_e32 v173, v95, v173
	v_add_f32_e32 v176, v96, v176
	s_waitcnt lgkmcnt(5)
	v_mfma_f32_32x32x16_bf16 v[34:49], v[230:233], v[110:113], v[34:49]
	ds_read_b128 v[230:233], v243 offset:57888
	v_add_f32_e32 v179, v97, v179
	v_cvt_pk_bf16_f32 v184, v66, v67
	v_cvt_pk_bf16_f32 v185, v68, v69
	v_cvt_pk_bf16_f32 v186, v70, v71
	v_cvt_pk_bf16_f32 v187, v72, v73
	v_cvt_pk_bf16_f32 v188, v74, v75
	v_cvt_pk_bf16_f32 v189, v76, v77
	s_waitcnt lgkmcnt(5)
	v_mfma_f32_32x32x16_bf16 v[34:49], v[234:237], v[114:117], v[34:49]
	ds_read_b128 v[234:237], v243 offset:53312
	v_cvt_pk_bf16_f32 v190, v78, v79
	v_cvt_pk_bf16_f32 v191, v80, v81
	v_add_f32_e32 v172, v66, v172
	v_add_f32_e32 v173, v67, v173
	v_add_f32_e32 v176, v68, v176
	v_add_f32_e32 v179, v69, v179
	v_add_f32_e32 v172, v70, v172
	s_waitcnt lgkmcnt(5)
	v_mfma_f32_32x32x16_bf16 v[34:49], v[244:247], v[118:121], v[34:49]
	ds_read_b128 v[244:247], v243 offset:57920
	v_add_f32_e32 v173, v71, v173
	v_add_f32_e32 v176, v72, v176
	v_add_f32_e32 v179, v73, v179
	v_add_f32_e32 v172, v74, v172
	v_add_f32_e32 v173, v75, v173
	v_add_f32_e32 v176, v76, v176
	v_add_f32_e32 v179, v77, v179
	s_waitcnt lgkmcnt(5)
	v_mfma_f32_32x32x16_bf16 v[18:33], v[196:199], v[168:171], v[18:33]
	ds_read_b128 v[196:199], v243 offset:53344
	v_add_f32_e32 v172, v78, v172
	v_add_f32_e32 v173, v79, v173
	v_add_f32_e32 v176, v80, v176
	v_add_f32_e32 v179, v81, v179
	v_add_f32_e32 v172, v172, v173
	v_add_f32_e32 v176, v176, v179
	v_max3_f32 v248, v50, v51, v52
	s_waitcnt lgkmcnt(5)
	v_mfma_f32_32x32x16_bf16 v[2:17], v[200:203], v[168:171], v[2:17]
	ds_read_b128 v[200:203], v243 offset:57952
	v_max3_f32 v249, v57, v58, v59
	v_max3_f32 v248, v248, v53, v54
	v_max3_f32 v249, v249, v60, v61
	v_max3_f32 v248, v248, v55, v56
	v_max3_f32 v249, v249, v62, v63
	s_waitcnt lgkmcnt(5)
	v_mfma_f32_32x32x16_bf16 v[18:33], v[216:219], v[180:183], v[18:33]
	v_max3_f32 v250, v34, v35, v36
	v_max3_f32 v251, v41, v42, v43
	v_max3_f32 v250, v250, v37, v38
	v_max3_f32 v251, v251, v44, v45
	v_max3_f32 v250, v250, v39, v40
	v_max3_f32 v251, v251, v46, v47
	v_max3_f32 v248, v248, v249, v64
	s_waitcnt lgkmcnt(4)
	v_mfma_f32_32x32x16_bf16 v[2:17], v[230:233], v[180:183], v[2:17]
	v_max3_f32 v250, v250, v251, v48
	v_max3_f32 v248, v248, v65, v49
	v_max_f32_e32 v248, v248, v250
	v_mov_b32_e32 v249, v248
	s_waitcnt lgkmcnt(3)
	v_mfma_f32_32x32x16_bf16 v[18:33], v[234:237], v[184:187], v[18:33]
	s_waitcnt lgkmcnt(2)
	v_mfma_f32_32x32x16_bf16 v[2:17], v[244:247], v[184:187], v[2:17]
	s_waitcnt lgkmcnt(1)
	v_mfma_f32_32x32x16_bf16 v[18:33], v[196:199], v[188:191], v[18:33]
	s_waitcnt lgkmcnt(0)
	v_mfma_f32_32x32x16_bf16 v[2:17], v[200:203], v[188:191], v[2:17]
	v_add_f32_e32 v0, v172, v176
	v_add_f32_e32 v161, v161, v0
	v_permlane32_swap_b32 v248, v249
	v_max_f32_e32 v174, v248, v249
	s_setprio 0
	s_cmp_lg_u32 s32, 0
	s_cbranch_scc1 .Lfb_b1
	s_waitcnt lgkmcnt(0)
	s_barrier
